# compress-MLP layer-1 tile: loads of 8 K-steps kept in flight (rolling) instead of two load-wait round trips per MFMA
# baseline (speedup 1.0000x reference)
; #define LAS __attribute__((address_space(3)))
; #define UNPACK8(v, f) do { _Pragma("unroll") for (int _e = 0; _e < 8; ++_e) (f)[_e] = bf2f((unsigned short)(v)[_e]); } while (0)
; __device__ __forceinline__ bf16x8 pack8(const float* f) { u32x4 w; w.x = pk2(f[0], f[1]); w.y = pk2(f[2], f[3]); w.z = pk2(f[4], f[5]); w.w = pk2(f[6], f[7]); return __builtin_bit_cast(bf16x8, w); }
; __device__ __forceinline__ void cmp_l1_tile(int t, const bf16_t* Z, const float* pek, const float* pev, const bf16_t* W1KT, const bf16_t* W1VT, float* HIDC, LAS float* part, int tid, int wave, int lane) {
;     const int ct = t & 3, rt = (t >> 2) & 3, g = (t >> 4) & 1, bl = (t >> 5) & 3, kv = t >> 7;
;     const float* pe = kv ? pev : pek; const bf16_t* W = kv ? W1VT : W1KT; const int col = (kv ? ZCV : ZCK) + g * 64;
;     const int h = lane >> 5, c = lane & 31, n = 32 * rt + c;
;     const bf16_t* wrow = W + (size_t)(32 * ct + c) * 2048 + 8 * h;
;     f32x16 acc;
; #pragma unroll
;     for (int r = 0; r < 16; ++r) acc[r] = 0.f;
; #pragma unroll
;     for (int li = 0; li < 4; ++li) {
;         const int l = 4 * wave + li;
;         int tokc = 16 * n + l; tokc = tokc > 2047 ? 2047 : tokc;
;         const bf16_t* arow = Z + ((size_t)bl * 2048 + tokc) * NINP + col + 8 * h;
;         const float* prow = pe + l * 64 + 8 * h;
; #pragma unroll
;         for (int q = 0; q < 4; ++q) {
;             const bf16x8 av = *(const bf16x8*)(arow + 16 * q); const f32x4 p0 = *(const f32x4*)(prow + 16 * q), p1 = *(const f32x4*)(prow + 16 * q + 4);
;             float f[8]; UNPACK8(av, f);
;             f[0] += p0.x; f[1] += p0.y; f[2] += p0.z; f[3] += p0.w; f[4] += p1.x; f[5] += p1.y; f[6] += p1.z; f[7] += p1.w;
;             const bf16x8 af = pack8(f);
;             const bf16x8 bfr = *(const bf16x8*)(wrow + (size_t)(l * 64 + 16 * q));
;             acc = __builtin_amdgcn_mfma_f32_32x32x16_bf16(af, bfr, acc, 0, 0, 0);
;         }
.LBB0_271:
	s_bfe_u32 s12, s28, 0x20005
	s_cmpk_lt_u32 s28, 0x80
	s_brev_b32 s0, 64
	s_cselect_b32 s0, s0, 0x2080000
	s_movk_i32 s1, 0x1340
	s_waitcnt lgkmcnt(0)
	s_cselect_b32 s21, s5, s7
	s_cselect_b32 s20, s4, s6
	s_cselect_b32 s31, s1, 0x1440
	s_add_u32 s0, s90, s0
	s_addc_u32 s1, s91, 0
	s_and_b32 s13, s26, 0x60
	s_and_b32 s30, s27, 0x60
	v_or_b32_e32 v0, s13, v30
	v_or_b32_e32 v4, s30, v30
	v_lshlrev_b32_e32 v0, 12, v0
	s_add_u32 s20, s20, s8
	v_lshl_add_u64 v[2:3], s[0:1], 0, v[0:1]
	v_lshlrev_b32_e32 v0, 4, v4
	s_addc_u32 s21, s21, s9
	v_lshl_add_u64 v[24:25], v[18:19], 1, v[2:3]
	s_lshl_b32 s0, s28, 3
	v_add_u32_e32 v2, s22, v0
	s_and_b32 s29, s0, 0x80
	v_min_i32_e32 v2, 0x7ff, v2
	s_lshl_b32 s92, s12, 11
	s_or_b32 s0, s29, s31
	s_mov_b32 s1, s93
	v_ashrrev_i32_e32 v3, 31, v2
	v_lshl_add_u64 v[28:29], v[20:21], 0, s[0:1]
	v_lshl_add_u64 v[2:3], v[2:3], 0, s[92:93]
	v_mad_u64_u32 v[50:51], s[0:1], v2, s97, v[28:29]
	v_lshl_add_u64 v[26:27], v[18:19], 2, s[20:21]
	v_mad_i32_i24 v51, v3, s97, v51
	v_lshl_add_u64 v[52:53], s[10:11], 2, v[26:27]
	v_lshl_add_u64 v[54:55], s[10:11], 1, v[24:25]
	s_ashr_i32 s20, s28, 7
	s_ashr_i32 s21, s20, 31
	s_lshl_b64 s[20:21], s[20:21], 10
	s_add_i32 s28, s28, s82
	s_add_i32 s26, s26, s34
	s_add_i32 s27, s27, s78
	v_add_u32_e32 v124, s23, v0
	v_min_i32_e32 v124, 0x7ff, v124
	v_ashrrev_i32_e32 v125, 31, v124
	v_lshl_add_u64 v[124:125], v[124:125], 0, s[92:93]
	v_mad_u64_u32 v[126:127], s[0:1], v124, s97, v[28:29]
	v_mad_i32_i24 v127, v125, s97, v127
	v_add_u32_e32 v124, s24, v0
	v_min_i32_e32 v124, 0x7ff, v124
	v_ashrrev_i32_e32 v125, 31, v124
	v_lshl_add_u64 v[124:125], v[124:125], 0, s[92:93]
	v_mad_u64_u32 v[128:129], s[0:1], v124, s97, v[28:29]
	v_mad_i32_i24 v129, v125, s97, v129
	v_add_u32_e32 v124, s25, v0
	v_min_i32_e32 v124, 0x7ff, v124
	v_ashrrev_i32_e32 v125, 31, v124
	v_lshl_add_u64 v[124:125], v[124:125], 0, s[92:93]
	v_mad_u64_u32 v[198:199], s[0:1], v124, s97, v[28:29]
	v_mad_i32_i24 v199, v125, s97, v199
	v_or_b32_e32 v0, s30, v31
	s_lshl_b32 s0, s12, 8
	s_or_b32 s0, s0, s29
	s_or_b32 s20, s20, s0
	s_lshl_b32 s92, s13, 2
	s_cmpk_lt_i32 s28, 0x100
	global_load_dwordx4 v[58:61], v[50:51], off
	global_load_dwordx4 v[62:65], v[52:53], off offset:16
	global_load_dwordx4 v[66:69], v[52:53], off
	global_load_dwordx4 v[70:73], v[54:55], off
	global_load_dwordx4 v[74:77], v[50:51], off offset:32
	global_load_dwordx4 v[78:81], v[52:53], off offset:80
	global_load_dwordx4 v[82:85], v[52:53], off offset:64
	global_load_dwordx4 v[86:89], v[54:55], off offset:32
	global_load_dwordx4 v[90:93], v[50:51], off offset:64
	global_load_dwordx4 v[94:97], v[52:53], off offset:144
	global_load_dwordx4 v[98:101], v[52:53], off offset:128
	global_load_dwordx4 v[102:105], v[54:55], off offset:64
	global_load_dwordx4 v[106:109], v[50:51], off offset:96
	global_load_dwordx4 v[110:113], v[52:53], off offset:208
	global_load_dwordx4 v[114:117], v[52:53], off offset:192
	global_load_dwordx4 v[118:121], v[54:55], off offset:96
	global_load_dwordx4 v[132:135], v[126:127], off
	global_load_dwordx4 v[136:139], v[52:53], off offset:272
	global_load_dwordx4 v[140:143], v[52:53], off offset:256
	global_load_dwordx4 v[144:147], v[54:55], off offset:128
	global_load_dwordx4 v[148:151], v[126:127], off offset:32
	global_load_dwordx4 v[152:155], v[52:53], off offset:336
	global_load_dwordx4 v[156:159], v[52:53], off offset:320
	global_load_dwordx4 v[160:163], v[54:55], off offset:160
	global_load_dwordx4 v[164:167], v[126:127], off offset:64
	global_load_dwordx4 v[168:171], v[52:53], off offset:400
	global_load_dwordx4 v[172:175], v[52:53], off offset:384
	global_load_dwordx4 v[176:179], v[54:55], off offset:192
	global_load_dwordx4 v[180:183], v[126:127], off offset:96
	global_load_dwordx4 v[184:187], v[52:53], off offset:464
	global_load_dwordx4 v[188:191], v[52:53], off offset:448
	global_load_dwordx4 v[192:195], v[54:55], off offset:224
	s_waitcnt vmcnt(28)
	v_lshlrev_b32_e32 v122, 16, v58
	v_and_b32_e32 v123, 0xffff0000, v58
	v_pk_add_f32 v[66:67], v[66:67], v[122:123]
	v_lshlrev_b32_e32 v122, 16, v59
	v_and_b32_e32 v123, 0xffff0000, v59
	v_pk_add_f32 v[68:69], v[68:69], v[122:123]
	v_lshlrev_b32_e32 v122, 16, v60
	v_and_b32_e32 v123, 0xffff0000, v60
	v_pk_add_f32 v[62:63], v[62:63], v[122:123]
	v_lshlrev_b32_e32 v122, 16, v61
	v_and_b32_e32 v123, 0xffff0000, v61
	v_pk_add_f32 v[64:65], v[64:65], v[122:123]
	v_cvt_pk_bf16_f32 v58, v66, v67
	v_cvt_pk_bf16_f32 v59, v68, v69
	v_cvt_pk_bf16_f32 v60, v62, v63
	v_cvt_pk_bf16_f32 v61, v64, v65
	s_nop 1
	v_mfma_f32_32x32x16_bf16 v[2:17], v[58:61], v[70:73], 0
	global_load_dwordx4 v[58:61], v[128:129], off
	global_load_dwordx4 v[62:65], v[52:53], off offset:528
	global_load_dwordx4 v[66:69], v[52:53], off offset:512
	global_load_dwordx4 v[70:73], v[54:55], off offset:256
	s_waitcnt vmcnt(28)
	v_lshlrev_b32_e32 v122, 16, v74
	v_and_b32_e32 v123, 0xffff0000, v74
	v_pk_add_f32 v[82:83], v[82:83], v[122:123]
	v_lshlrev_b32_e32 v122, 16, v75
	v_and_b32_e32 v123, 0xffff0000, v75
	v_pk_add_f32 v[84:85], v[84:85], v[122:123]
	v_lshlrev_b32_e32 v122, 16, v76
	v_and_b32_e32 v123, 0xffff0000, v76
	v_pk_add_f32 v[78:79], v[78:79], v[122:123]
	v_lshlrev_b32_e32 v122, 16, v77
	v_and_b32_e32 v123, 0xffff0000, v77
	v_pk_add_f32 v[80:81], v[80:81], v[122:123]
	v_cvt_pk_bf16_f32 v74, v82, v83
	v_cvt_pk_bf16_f32 v75, v84, v85
	v_cvt_pk_bf16_f32 v76, v78, v79
	v_cvt_pk_bf16_f32 v77, v80, v81
	s_nop 1
	v_mfma_f32_32x32x16_bf16 v[2:17], v[74:77], v[86:89], v[2:17]
	global_load_dwordx4 v[74:77], v[128:129], off offset:32
	global_load_dwordx4 v[78:81], v[52:53], off offset:592
	global_load_dwordx4 v[82:85], v[52:53], off offset:576
	global_load_dwordx4 v[86:89], v[54:55], off offset:288
	s_waitcnt vmcnt(28)
; #define UNPACK8(v, f) do { _Pragma("unroll") for (int _e = 0; _e < 8; ++_e) (f)[_e] = bf2f((unsigned short)(v)[_e]); } while (0)
; __device__ __forceinline__ bf16x8 pack8(const float* f) { u32x4 w; w.x = pk2(f[0], f[1]); w.y = pk2(f[2], f[3]); w.z = pk2(f[4], f[5]); w.w = pk2(f[6], f[7]); return __builtin_bit_cast(bf16x8, w); }
; __device__ __forceinline__ void cmp_l1_tile(int t, const bf16_t* Z, const float* pek, const float* pev, const bf16_t* W1KT, const bf16_t* W1VT, float* HIDC, LAS float* part, int tid, int wave, int lane) {
;     ...
;     for (int li = 0; li < 4; ++li) {
;         const int l = 4 * wave + li;
;         int tokc = 16 * n + l; tokc = tokc > 2047 ? 2047 : tokc;
;         const bf16_t* arow = Z + ((size_t)bl * 2048 + tokc) * NINP + col + 8 * h;
;         const float* prow = pe + l * 64 + 8 * h;
; #pragma unroll
;         for (int q = 0; q < 4; ++q) {
;             const bf16x8 av = *(const bf16x8*)(arow + 16 * q); const f32x4 p0 = *(const f32x4*)(prow + 16 * q), p1 = *(const f32x4*)(prow + 16 * q + 4);
;             float f[8]; UNPACK8(av, f);
;             f[0] += p0.x; f[1] += p0.y; f[2] += p0.z; f[3] += p0.w; f[4] += p1.x; f[5] += p1.y; f[6] += p1.z; f[7] += p1.w;
;             const bf16x8 af = pack8(f);
;             const bf16x8 bfr = *(const bf16x8*)(wrow + (size_t)(l * 64 + 16 * q));
;             acc = __builtin_amdgcn_mfma_f32_32x32x16_bf16(af, bfr, acc, 0, 0, 0);
;         }
	v_lshlrev_b32_e32 v122, 16, v90
	v_and_b32_e32 v123, 0xffff0000, v90
	v_pk_add_f32 v[98:99], v[98:99], v[122:123]
	v_lshlrev_b32_e32 v122, 16, v91
	v_and_b32_e32 v123, 0xffff0000, v91
	v_pk_add_f32 v[100:101], v[100:101], v[122:123]
	v_lshlrev_b32_e32 v122, 16, v92
	v_and_b32_e32 v123, 0xffff0000, v92
	v_pk_add_f32 v[94:95], v[94:95], v[122:123]
	v_lshlrev_b32_e32 v122, 16, v93
	v_and_b32_e32 v123, 0xffff0000, v93
	v_pk_add_f32 v[96:97], v[96:97], v[122:123]
	v_cvt_pk_bf16_f32 v90, v98, v99
	v_cvt_pk_bf16_f32 v91, v100, v101
	v_cvt_pk_bf16_f32 v92, v94, v95
	v_cvt_pk_bf16_f32 v93, v96, v97
	s_nop 1
	v_mfma_f32_32x32x16_bf16 v[2:17], v[90:93], v[102:105], v[2:17]
	global_load_dwordx4 v[90:93], v[128:129], off offset:64
	global_load_dwordx4 v[94:97], v[52:53], off offset:656
	global_load_dwordx4 v[98:101], v[52:53], off offset:640
	global_load_dwordx4 v[102:105], v[54:55], off offset:320
	s_waitcnt vmcnt(28)
	v_lshlrev_b32_e32 v122, 16, v106
	v_and_b32_e32 v123, 0xffff0000, v106
	v_pk_add_f32 v[114:115], v[114:115], v[122:123]
	v_lshlrev_b32_e32 v122, 16, v107
	v_and_b32_e32 v123, 0xffff0000, v107
	v_pk_add_f32 v[116:117], v[116:117], v[122:123]
	v_lshlrev_b32_e32 v122, 16, v108
	v_and_b32_e32 v123, 0xffff0000, v108
	v_pk_add_f32 v[110:111], v[110:111], v[122:123]
	v_lshlrev_b32_e32 v122, 16, v109
	v_and_b32_e32 v123, 0xffff0000, v109
	v_pk_add_f32 v[112:113], v[112:113], v[122:123]
	v_cvt_pk_bf16_f32 v106, v114, v115
	v_cvt_pk_bf16_f32 v107, v116, v117
	v_cvt_pk_bf16_f32 v108, v110, v111
	v_cvt_pk_bf16_f32 v109, v112, v113
	s_nop 1
	v_mfma_f32_32x32x16_bf16 v[2:17], v[106:109], v[118:121], v[2:17]
	global_load_dwordx4 v[106:109], v[128:129], off offset:96
	global_load_dwordx4 v[110:113], v[52:53], off offset:720
	global_load_dwordx4 v[114:117], v[52:53], off offset:704
	global_load_dwordx4 v[118:121], v[54:55], off offset:352
	s_waitcnt vmcnt(28)
	v_lshlrev_b32_e32 v122, 16, v132
	v_and_b32_e32 v123, 0xffff0000, v132
	v_pk_add_f32 v[140:141], v[140:141], v[122:123]
	v_lshlrev_b32_e32 v122, 16, v133
	v_and_b32_e32 v123, 0xffff0000, v133
	v_pk_add_f32 v[142:143], v[142:143], v[122:123]
	v_lshlrev_b32_e32 v122, 16, v134
	v_and_b32_e32 v123, 0xffff0000, v134
	v_pk_add_f32 v[136:137], v[136:137], v[122:123]
	v_lshlrev_b32_e32 v122, 16, v135
	v_and_b32_e32 v123, 0xffff0000, v135
	v_pk_add_f32 v[138:139], v[138:139], v[122:123]
	v_cvt_pk_bf16_f32 v132, v140, v141
	v_cvt_pk_bf16_f32 v133, v142, v143
	v_cvt_pk_bf16_f32 v134, v136, v137
	v_cvt_pk_bf16_f32 v135, v138, v139
	s_nop 1
	v_mfma_f32_32x32x16_bf16 v[2:17], v[132:135], v[144:147], v[2:17]
	global_load_dwordx4 v[132:135], v[198:199], off
	global_load_dwordx4 v[136:139], v[52:53], off offset:784
	global_load_dwordx4 v[140:143], v[52:53], off offset:768
	global_load_dwordx4 v[144:147], v[54:55], off offset:384
	s_waitcnt vmcnt(28)
	v_lshlrev_b32_e32 v122, 16, v148
	v_and_b32_e32 v123, 0xffff0000, v148
	v_pk_add_f32 v[156:157], v[156:157], v[122:123]
	v_lshlrev_b32_e32 v122, 16, v149
	v_and_b32_e32 v123, 0xffff0000, v149
	v_pk_add_f32 v[158:159], v[158:159], v[122:123]
	v_lshlrev_b32_e32 v122, 16, v150
	v_and_b32_e32 v123, 0xffff0000, v150
	v_pk_add_f32 v[152:153], v[152:153], v[122:123]
	v_lshlrev_b32_e32 v122, 16, v151
	v_and_b32_e32 v123, 0xffff0000, v151
	v_pk_add_f32 v[154:155], v[154:155], v[122:123]
	v_cvt_pk_bf16_f32 v148, v156, v157
	v_cvt_pk_bf16_f32 v149, v158, v159
	v_cvt_pk_bf16_f32 v150, v152, v153
	v_cvt_pk_bf16_f32 v151, v154, v155
	s_nop 1
	v_mfma_f32_32x32x16_bf16 v[2:17], v[148:151], v[160:163], v[2:17]
	global_load_dwordx4 v[148:151], v[198:199], off offset:32
	global_load_dwordx4 v[152:155], v[52:53], off offset:848
	global_load_dwordx4 v[156:159], v[52:53], off offset:832
	global_load_dwordx4 v[160:163], v[54:55], off offset:416
	s_waitcnt vmcnt(28)
	v_lshlrev_b32_e32 v122, 16, v164
	v_and_b32_e32 v123, 0xffff0000, v164
	v_pk_add_f32 v[172:173], v[172:173], v[122:123]
	v_lshlrev_b32_e32 v122, 16, v165
	v_and_b32_e32 v123, 0xffff0000, v165
	v_pk_add_f32 v[174:175], v[174:175], v[122:123]
	v_lshlrev_b32_e32 v122, 16, v166
	v_and_b32_e32 v123, 0xffff0000, v166
	v_pk_add_f32 v[168:169], v[168:169], v[122:123]
	v_lshlrev_b32_e32 v122, 16, v167
	v_and_b32_e32 v123, 0xffff0000, v167
	v_pk_add_f32 v[170:171], v[170:171], v[122:123]
	v_cvt_pk_bf16_f32 v164, v172, v173
	v_cvt_pk_bf16_f32 v165, v174, v175
	v_cvt_pk_bf16_f32 v166, v168, v169
	v_cvt_pk_bf16_f32 v167, v170, v171
	s_nop 1
	v_mfma_f32_32x32x16_bf16 v[2:17], v[164:167], v[176:179], v[2:17]
	global_load_dwordx4 v[164:167], v[198:199], off offset:64
	global_load_dwordx4 v[168:171], v[52:53], off offset:912
	global_load_dwordx4 v[172:175], v[52:53], off offset:896
	global_load_dwordx4 v[176:179], v[54:55], off offset:448
	s_waitcnt vmcnt(28)
	v_lshlrev_b32_e32 v122, 16, v180
	v_and_b32_e32 v123, 0xffff0000, v180
	v_pk_add_f32 v[188:189], v[188:189], v[122:123]
	v_lshlrev_b32_e32 v122, 16, v181
	v_and_b32_e32 v123, 0xffff0000, v181
	v_pk_add_f32 v[190:191], v[190:191], v[122:123]
	v_lshlrev_b32_e32 v122, 16, v182
	v_and_b32_e32 v123, 0xffff0000, v182
	v_pk_add_f32 v[184:185], v[184:185], v[122:123]
	v_lshlrev_b32_e32 v122, 16, v183
	v_and_b32_e32 v123, 0xffff0000, v183
	v_pk_add_f32 v[186:187], v[186:187], v[122:123]
	v_cvt_pk_bf16_f32 v180, v188, v189
	v_cvt_pk_bf16_f32 v181, v190, v191
	v_cvt_pk_bf16_f32 v182, v184, v185
	v_cvt_pk_bf16_f32 v183, v186, v187
	s_nop 1
	v_mfma_f32_32x32x16_bf16 v[2:17], v[180:183], v[192:195], v[2:17]
	global_load_dwordx4 v[180:183], v[198:199], off offset:96
	global_load_dwordx4 v[184:187], v[52:53], off offset:976
	global_load_dwordx4 v[188:191], v[52:53], off offset:960
	global_load_dwordx4 v[192:195], v[54:55], off offset:480
	s_waitcnt vmcnt(28)
; #define UNPACK8(v, f) do { _Pragma("unroll") for (int _e = 0; _e < 8; ++_e) (f)[_e] = bf2f((unsigned short)(v)[_e]); } while (0)
; __device__ __forceinline__ bf16x8 pack8(const float* f) { u32x4 w; w.x = pk2(f[0], f[1]); w.y = pk2(f[2], f[3]); w.z = pk2(f[4], f[5]); w.w = pk2(f[6], f[7]); return __builtin_bit_cast(bf16x8, w); }
; __device__ __forceinline__ void cmp_l1_tile(int t, const bf16_t* Z, const float* pek, const float* pev, const bf16_t* W1KT, const bf16_t* W1VT, float* HIDC, LAS float* part, int tid, int wave, int lane) {
;     ...
;     for (int li = 0; li < 4; ++li) {
;         const int l = 4 * wave + li;
;         int tokc = 16 * n + l; tokc = tokc > 2047 ? 2047 : tokc;
;         const bf16_t* arow = Z + ((size_t)bl * 2048 + tokc) * NINP + col + 8 * h;
;         const float* prow = pe + l * 64 + 8 * h;
; #pragma unroll
;         for (int q = 0; q < 4; ++q) {
;             const bf16x8 av = *(const bf16x8*)(arow + 16 * q); const f32x4 p0 = *(const f32x4*)(prow + 16 * q), p1 = *(const f32x4*)(prow + 16 * q + 4);
;             float f[8]; UNPACK8(av, f);
;             f[0] += p0.x; f[1] += p0.y; f[2] += p0.z; f[3] += p0.w; f[4] += p1.x; f[5] += p1.y; f[6] += p1.z; f[7] += p1.w;
;             const bf16x8 af = pack8(f);
;             const bf16x8 bfr = *(const bf16x8*)(wrow + (size_t)(l * 64 + 16 * q));
;             acc = __builtin_amdgcn_mfma_f32_32x32x16_bf16(af, bfr, acc, 0, 0, 0);
;         }
;     }
;     __syncthreads();
	v_lshlrev_b32_e32 v122, 16, v58
	v_and_b32_e32 v123, 0xffff0000, v58
	v_pk_add_f32 v[66:67], v[66:67], v[122:123]
	v_lshlrev_b32_e32 v122, 16, v59
	v_and_b32_e32 v123, 0xffff0000, v59
	v_pk_add_f32 v[68:69], v[68:69], v[122:123]
	v_lshlrev_b32_e32 v122, 16, v60
	v_and_b32_e32 v123, 0xffff0000, v60
	v_pk_add_f32 v[62:63], v[62:63], v[122:123]
	v_lshlrev_b32_e32 v122, 16, v61
	v_and_b32_e32 v123, 0xffff0000, v61
	v_pk_add_f32 v[64:65], v[64:65], v[122:123]
	v_cvt_pk_bf16_f32 v58, v66, v67
	v_cvt_pk_bf16_f32 v59, v68, v69
	v_cvt_pk_bf16_f32 v60, v62, v63
	v_cvt_pk_bf16_f32 v61, v64, v65
	s_nop 1
	v_mfma_f32_32x32x16_bf16 v[2:17], v[58:61], v[70:73], v[2:17]
	s_waitcnt vmcnt(24)
	v_lshlrev_b32_e32 v122, 16, v74
	v_and_b32_e32 v123, 0xffff0000, v74
	v_pk_add_f32 v[82:83], v[82:83], v[122:123]
	v_lshlrev_b32_e32 v122, 16, v75
	v_and_b32_e32 v123, 0xffff0000, v75
	v_pk_add_f32 v[84:85], v[84:85], v[122:123]
	v_lshlrev_b32_e32 v122, 16, v76
	v_and_b32_e32 v123, 0xffff0000, v76
	v_pk_add_f32 v[78:79], v[78:79], v[122:123]
	v_lshlrev_b32_e32 v122, 16, v77
	v_and_b32_e32 v123, 0xffff0000, v77
	v_pk_add_f32 v[80:81], v[80:81], v[122:123]
	v_cvt_pk_bf16_f32 v74, v82, v83
	v_cvt_pk_bf16_f32 v75, v84, v85
	v_cvt_pk_bf16_f32 v76, v78, v79
	v_cvt_pk_bf16_f32 v77, v80, v81
	s_nop 1
	v_mfma_f32_32x32x16_bf16 v[2:17], v[74:77], v[86:89], v[2:17]
	s_waitcnt vmcnt(20)
	v_lshlrev_b32_e32 v122, 16, v90
	v_and_b32_e32 v123, 0xffff0000, v90
	v_pk_add_f32 v[98:99], v[98:99], v[122:123]
	v_lshlrev_b32_e32 v122, 16, v91
	v_and_b32_e32 v123, 0xffff0000, v91
	v_pk_add_f32 v[100:101], v[100:101], v[122:123]
	v_lshlrev_b32_e32 v122, 16, v92
	v_and_b32_e32 v123, 0xffff0000, v92
	v_pk_add_f32 v[94:95], v[94:95], v[122:123]
	v_lshlrev_b32_e32 v122, 16, v93
	v_and_b32_e32 v123, 0xffff0000, v93
	v_pk_add_f32 v[96:97], v[96:97], v[122:123]
	v_cvt_pk_bf16_f32 v90, v98, v99
	v_cvt_pk_bf16_f32 v91, v100, v101
	v_cvt_pk_bf16_f32 v92, v94, v95
	v_cvt_pk_bf16_f32 v93, v96, v97
	s_nop 1
	v_mfma_f32_32x32x16_bf16 v[2:17], v[90:93], v[102:105], v[2:17]
	s_waitcnt vmcnt(16)
	v_lshlrev_b32_e32 v122, 16, v106
	v_and_b32_e32 v123, 0xffff0000, v106
	v_pk_add_f32 v[114:115], v[114:115], v[122:123]
	v_lshlrev_b32_e32 v122, 16, v107
	v_and_b32_e32 v123, 0xffff0000, v107
	v_pk_add_f32 v[116:117], v[116:117], v[122:123]
	v_lshlrev_b32_e32 v122, 16, v108
	v_and_b32_e32 v123, 0xffff0000, v108
	v_pk_add_f32 v[110:111], v[110:111], v[122:123]
	v_lshlrev_b32_e32 v122, 16, v109
	v_and_b32_e32 v123, 0xffff0000, v109
	v_pk_add_f32 v[112:113], v[112:113], v[122:123]
	v_cvt_pk_bf16_f32 v106, v114, v115
	v_cvt_pk_bf16_f32 v107, v116, v117
	v_cvt_pk_bf16_f32 v108, v110, v111
	v_cvt_pk_bf16_f32 v109, v112, v113
	s_nop 1
	v_mfma_f32_32x32x16_bf16 v[2:17], v[106:109], v[118:121], v[2:17]
	s_waitcnt vmcnt(12)
	v_lshlrev_b32_e32 v122, 16, v132
	v_and_b32_e32 v123, 0xffff0000, v132
	v_pk_add_f32 v[140:141], v[140:141], v[122:123]
	v_lshlrev_b32_e32 v122, 16, v133
	v_and_b32_e32 v123, 0xffff0000, v133
	v_pk_add_f32 v[142:143], v[142:143], v[122:123]
	v_lshlrev_b32_e32 v122, 16, v134
	v_and_b32_e32 v123, 0xffff0000, v134
	v_pk_add_f32 v[136:137], v[136:137], v[122:123]
	v_lshlrev_b32_e32 v122, 16, v135
	v_and_b32_e32 v123, 0xffff0000, v135
	v_pk_add_f32 v[138:139], v[138:139], v[122:123]
	v_cvt_pk_bf16_f32 v132, v140, v141
	v_cvt_pk_bf16_f32 v133, v142, v143
	v_cvt_pk_bf16_f32 v134, v136, v137
	v_cvt_pk_bf16_f32 v135, v138, v139
	s_nop 1
	v_mfma_f32_32x32x16_bf16 v[2:17], v[132:135], v[144:147], v[2:17]
	s_waitcnt vmcnt(8)
	v_lshlrev_b32_e32 v122, 16, v148
	v_and_b32_e32 v123, 0xffff0000, v148
	v_pk_add_f32 v[156:157], v[156:157], v[122:123]
	v_lshlrev_b32_e32 v122, 16, v149
	v_and_b32_e32 v123, 0xffff0000, v149
	v_pk_add_f32 v[158:159], v[158:159], v[122:123]
	v_lshlrev_b32_e32 v122, 16, v150
	v_and_b32_e32 v123, 0xffff0000, v150
	v_pk_add_f32 v[152:153], v[152:153], v[122:123]
	v_lshlrev_b32_e32 v122, 16, v151
	v_and_b32_e32 v123, 0xffff0000, v151
	v_pk_add_f32 v[154:155], v[154:155], v[122:123]
	v_cvt_pk_bf16_f32 v148, v156, v157
	v_cvt_pk_bf16_f32 v149, v158, v159
	v_cvt_pk_bf16_f32 v150, v152, v153
	v_cvt_pk_bf16_f32 v151, v154, v155
	s_nop 1
	v_mfma_f32_32x32x16_bf16 v[2:17], v[148:151], v[160:163], v[2:17]
	s_waitcnt vmcnt(4)
	v_lshlrev_b32_e32 v122, 16, v164
	v_and_b32_e32 v123, 0xffff0000, v164
	v_pk_add_f32 v[172:173], v[172:173], v[122:123]
	v_lshlrev_b32_e32 v122, 16, v165
	v_and_b32_e32 v123, 0xffff0000, v165
	v_pk_add_f32 v[174:175], v[174:175], v[122:123]
	v_lshlrev_b32_e32 v122, 16, v166
	v_and_b32_e32 v123, 0xffff0000, v166
	v_pk_add_f32 v[168:169], v[168:169], v[122:123]
	v_lshlrev_b32_e32 v122, 16, v167
	v_and_b32_e32 v123, 0xffff0000, v167
	v_pk_add_f32 v[170:171], v[170:171], v[122:123]
	v_cvt_pk_bf16_f32 v164, v172, v173
	v_cvt_pk_bf16_f32 v165, v174, v175
	v_cvt_pk_bf16_f32 v166, v168, v169
	v_cvt_pk_bf16_f32 v167, v170, v171
	s_nop 1
	v_mfma_f32_32x32x16_bf16 v[2:17], v[164:167], v[176:179], v[2:17]
	s_waitcnt vmcnt(0)
	v_lshlrev_b32_e32 v122, 16, v180
	v_and_b32_e32 v123, 0xffff0000, v180
	v_pk_add_f32 v[188:189], v[188:189], v[122:123]
	v_lshlrev_b32_e32 v122, 16, v181
	v_and_b32_e32 v123, 0xffff0000, v181
	v_pk_add_f32 v[190:191], v[190:191], v[122:123]
	v_lshlrev_b32_e32 v122, 16, v182
	v_and_b32_e32 v123, 0xffff0000, v182
	v_pk_add_f32 v[184:185], v[184:185], v[122:123]
	v_lshlrev_b32_e32 v122, 16, v183
	v_and_b32_e32 v123, 0xffff0000, v183
	v_pk_add_f32 v[186:187], v[186:187], v[122:123]
	v_cvt_pk_bf16_f32 v180, v188, v189
	v_cvt_pk_bf16_f32 v181, v190, v191
	v_cvt_pk_bf16_f32 v182, v184, v185
	v_cvt_pk_bf16_f32 v183, v186, v187
	s_barrier
; __device__ __forceinline__ float gelu_tanh(float x) { const float u = 0.7978845608028654f * (x + 0.044715f * x * x * x); const float t = 1.f - 2.f * __builtin_amdgcn_rcpf(__expf(2.f * u) + 1.f); return 0.5f * x * (1.f + t); }
; __device__ __forceinline__ void cmp_l1_tile(int t, const bf16_t* Z, const float* pek, const float* pev, const bf16_t* W1KT, const bf16_t* W1VT, float* HIDC, LAS float* part, int tid, int wave, int lane) {
;     ...
;             acc = __builtin_amdgcn_mfma_f32_32x32x16_bf16(af, bfr, acc, 0, 0, 0);
;         }
;     }
;     __syncthreads();
; #pragma unroll
;     for (int r = 0; r < 16; ++r) part[(wave * 16 + r) * 64 + lane] = acc[r];
;     __syncthreads();
; #pragma unroll
;     for (int k = 0; k < 2; ++k) { const int idx = tid + 512 * k, r = idx >> 6, ln = idx & 63; float s = 0.f;
; #pragma unroll
;         for (int w = 0; w < 8; ++w) s += part[(w * 16 + r) * 64 + ln];
;         const int nn = 32 * rt + (r & 3) + 8 * (r >> 2) + 4 * (ln >> 5);
;         HIDC[((size_t)kv * 1024 + (bl * 2 + g) * 128 + nn) * 128 + 32 * ct + (ln & 31)] = gelu_tanh(s); }
	s_nop 1
	v_mfma_f32_32x32x16_bf16 v[2:17], v[180:183], v[192:195], v[2:17]
	s_nop 11
	ds_write2st64_b32 v36, v2, v3 offset1:1
	ds_write2st64_b32 v36, v4, v5 offset0:2 offset1:3
	ds_write2st64_b32 v36, v6, v7 offset0:4 offset1:5
	ds_write2st64_b32 v36, v8, v9 offset0:6 offset1:7
	ds_write2st64_b32 v36, v10, v11 offset0:8 offset1:9
	ds_write2st64_b32 v36, v12, v13 offset0:10 offset1:11
	ds_write2st64_b32 v36, v14, v15 offset0:12 offset1:13
	ds_write2st64_b32 v36, v16, v17 offset0:14 offset1:15
	s_waitcnt lgkmcnt(0)
	s_barrier
	ds_read2st64_b32 v[4:5], v32 offset1:16
	v_lshl_add_u64 v[2:3], v[22:23], 0, s[92:93]
	s_waitcnt lgkmcnt(0)
	v_add_f32_e32 v4, 0, v4
	v_add_f32_e32 v6, v4, v5
	ds_read2st64_b32 v[4:5], v32 offset0:32 offset1:48
	s_waitcnt lgkmcnt(0)
	v_add_f32_e32 v4, v6, v4
	v_add_f32_e32 v6, v4, v5
	ds_read2st64_b32 v[4:5], v32 offset0:64 offset1:80
	s_waitcnt lgkmcnt(0)
	v_add_f32_e32 v4, v6, v4
	v_add_f32_e32 v6, v4, v5
	ds_read2st64_b32 v[4:5], v32 offset0:96 offset1:112
	s_waitcnt lgkmcnt(0)
	v_add_f32_e32 v4, v6, v4
	v_add_f32_e32 v5, v4, v5
	v_mul_f32_e32 v6, 0x3d372713, v5
	v_mul_f32_e32 v6, v5, v6
	v_fma_f32 v6, v5, v6, v5
	v_mul_f32_e32 v6, 0x3f4c422a, v6
	v_add_f32_e32 v6, v6, v6
	v_mul_f32_e32 v6, 0x3fb8aa3b, v6
	v_exp_f32_e32 v6, v6
	v_add_u32_e32 v4, v0, v33
	v_mul_f32_e32 v5, 0.5, v5
	v_add_f32_e32 v6, 1.0, v6
	v_rcp_f32_e32 v6, v6
	s_nop 0
	v_fma_f32 v6, v6, -2.0, 1.0
	v_add_f32_e32 v6, 1.0, v6
	v_mul_f32_e32 v6, v5, v6
	v_ashrrev_i32_e32 v5, 31, v4
	v_lshl_add_u64 v[4:5], s[20:21], 0, v[4:5]
	v_lshlrev_b64 v[4:5], 9, v[4:5]
	v_lshl_add_u64 v[4:5], v[2:3], 0, v[4:5]
	global_store_dword v[4:5], v6, off
	ds_read2st64_b32 v[4:5], v34 offset1:16
	s_waitcnt lgkmcnt(0)
	v_add_f32_e32 v4, 0, v4
	v_add_f32_e32 v6, v4, v5
	ds_read2st64_b32 v[4:5], v34 offset0:32 offset1:48
	s_waitcnt lgkmcnt(0)
	v_add_f32_e32 v4, v6, v4
	v_add_f32_e32 v6, v4, v5
	ds_read2st64_b32 v[4:5], v34 offset0:64 offset1:80
	s_waitcnt lgkmcnt(0)
	v_add_f32_e32 v4, v6, v4
	v_add_f32_e32 v6, v4, v5
	ds_read2st64_b32 v[4:5], v34 offset0:96 offset1:112
	s_waitcnt lgkmcnt(0)
	v_add_f32_e32 v4, v6, v4
	v_add_f32_e32 v5, v4, v5
	v_add_u32_e32 v4, v0, v35
	v_mul_f32_e32 v0, 0x3d372713, v5
	v_mul_f32_e32 v0, v5, v0
	v_fma_f32 v0, v5, v0, v5
	v_mul_f32_e32 v0, 0x3f4c422a, v0
	v_add_f32_e32 v0, v0, v0
	v_mul_f32_e32 v0, 0x3fb8aa3b, v0
	v_exp_f32_e32 v0, v0
	v_mul_f32_e32 v5, 0.5, v5
	v_add_f32_e32 v0, 1.0, v0
	v_rcp_f32_e32 v0, v0
	s_nop 0
	v_fma_f32 v0, v0, -2.0, 1.0
	v_add_f32_e32 v0, 1.0, v0
	v_mul_f32_e32 v0, v5, v0
	v_ashrrev_i32_e32 v5, 31, v4
	v_lshl_add_u64 v[4:5], s[20:21], 0, v[4:5]
	v_lshlrev_b64 v[4:5], 9, v[4:5]
	v_lshl_add_u64 v[2:3], v[2:3], 0, v[4:5]
	global_store_dword v[2:3], v0, off
	s_cbranch_scc1 .LBB0_271
